# v102 plus gate load hoisted in the token-0 dil combine loop (one fewer serialized load round trip per iteration)
# speedup vs baseline: 1.0203x; 1.0061x over previous
; DI float silu_f(float x) { return x / (1.0f + __expf(-x)); }
; DI void tok0_mix_dil(ldsp lds, const Params& p, const float* P, float* BRo, int task, int tid, int wid, int lane) {
;     ...
;         for (int c = tid; c < 768; c += 512) {
;             const int head = c >> 7;
;             const float l0 = S18[head], l1 = S18[6 + head], l2 = S18[12 + head];
;             const float m = fmaxf(l0, fmaxf(l1, l2));
;             float e0 = __expf(l0 - m), e1 = __expf(l1 - m), e2 = __expf(l2 - m);
;             const float is = 1.0f / (e0 + e1 + e2);
;             const float o = (e0 * pr[1536 + c] + e1 * pr[2304 + 1536 + c] + e2 * pr[4608 + 1536 + c]) * is;
;             BRo[(size_t)b * 1024 + c] = o * silu_f(pr[DB_GATE + c]);
;         }
.LBB0_122:
	v_ashrrev_i32_e32 v1, 7, v0
	v_lshl_add_u32 v1, v1, 2, 0
	v_add_u32_e32 v1, 0x10100, v1
	ds_read2_b32 v[2:3], v1 offset1:6
	ds_read_b32 v1, v1 offset:48
	s_mov_b32 s0, 0x35a9d000
	s_waitcnt lgkmcnt(0)
	v_max3_f32 v4, v2, v3, v1
	v_sub_f32_e32 v2, v2, v4
	v_mul_f32_e32 v2, 0x3fb8aa3b, v2
	v_exp_f32_e32 v5, v2
	v_sub_f32_e32 v2, v3, v4
	v_mul_f32_e32 v2, 0x3fb8aa3b, v2
	v_exp_f32_e32 v10, v2
	v_lshl_add_u64 v[2:3], s[36:37], 0, v[80:81]
	v_add_co_u32_e32 v6, vcc, s0, v2
	s_mov_b32 s0, 0x35a9f000
	s_nop 0
	v_addc_co_u32_e32 v7, vcc, 0, v3, vcc
	v_add_co_u32_e32 v8, vcc, s0, v2
	s_mov_b32 s0, 0x35aa3000
	s_nop 0
	v_addc_co_u32_e32 v9, vcc, 0, v3, vcc
	v_sub_f32_e32 v1, v1, v4
	v_add_co_u32_e32 v2, vcc, s0, v2
	v_mul_f32_e32 v1, 0x3fb8aa3b, v1
	s_nop 0
	v_addc_co_u32_e32 v3, vcc, 0, v3, vcc
	v_exp_f32_e32 v4, v1
	global_load_dword v7, v[6:7], off offset:2048
	v_add_f32_e32 v155, v5, v10
	global_load_dword v1, v[8:9], off offset:3072
	global_load_dword v6, v[2:3], off offset:-4096
	global_load_dword v11, v[2:3], off
	s_add_u32 s36, s36, 0x800
	s_addc_u32 s37, s37, 0
	s_movk_i32 s0, 0xff
	s_waitcnt vmcnt(1)
	v_pk_mul_f32 v[6:7], v[6:7], v[4:5]
	v_mov_b32_e32 v3, v4
	v_fma_f32 v1, v1, v10, v7
	v_add_f32_e32 v1, v6, v1
	s_waitcnt vmcnt(0)
	v_mul_f32_e32 v2, 0xbfb8aa3b, v11
	v_exp_f32_e32 v2, v2
	s_nop 0
	v_pk_add_f32 v[2:3], v[2:3], v[154:155]
	s_nop 0
	v_div_scale_f32 v4, s[22:23], v2, v2, v11
	v_rcp_f32_e32 v6, v4
	s_nop 0
	v_fma_f32 v7, -v4, v6, 1.0
	v_fmac_f32_e32 v6, v7, v6
	v_div_scale_f32 v7, vcc, v11, v2, v11
	v_mul_f32_e32 v8, v7, v6
	v_fma_f32 v9, -v4, v8, v7
	v_fmac_f32_e32 v8, v9, v6
	v_fma_f32 v4, -v4, v8, v7
	v_div_fmas_f32 v4, v4, v6, v8
	v_div_fixup_f32 v2, v4, v2, v11
	v_div_scale_f32 v4, s[22:23], v3, v3, 1.0
	v_rcp_f32_e32 v5, v4
	s_nop 0
	v_fma_f32 v6, -v4, v5, 1.0
	v_fmac_f32_e32 v5, v6, v5
	v_div_scale_f32 v6, vcc, 1.0, v3, 1.0
	v_mul_f32_e32 v7, v6, v5
	v_fma_f32 v8, -v4, v7, v6
	v_fmac_f32_e32 v7, v8, v5
	v_fma_f32 v4, -v4, v7, v6
	v_div_fmas_f32 v4, v4, v5, v7
	v_div_fixup_f32 v3, v4, v3, 1.0
	v_mul_f32_e32 v1, v1, v3
	v_mul_f32_e32 v1, v2, v1
	v_lshl_add_u64 v[2:3], s[30:31], 0, v[80:81]
	s_add_u32 s30, s30, 0x800
	global_store_dword v[2:3], v1, off
	v_add_u32_e32 v1, 0x200, v0
	s_addc_u32 s31, s31, 0
	v_cmp_lt_i32_e32 vcc, s0, v0
	s_or_b64 s[50:51], vcc, s[50:51]
	v_mov_b32_e32 v0, v1
	s_andn2_b64 exec, exec, s[50:51]
	s_cbranch_execnz .LBB0_122
	s_branch .LBB0_94
